# combination of five latency edits on top of the w_in batch version: q-epilogue rope-table prefetch before the store, KR rope rows batched, ada inner loop with plain fmac from ds_read_b64, swa K/V per-
# speedup vs baseline: 1.0043x; 1.0043x over previous
; DI void ada_tile(const Params& p, int layer, int cg64, char* lds) {
;     ...
; #pragma unroll 8
;   for (int kk = 0; kk < 256; ++kk) {
;     int k = kq * 256 + kk;
;     float wv = w[(size_t)k * 6144];
; #pragma unroll
;     for (int i = 0; i < 17; ++i) acc[i] += sc[i * 1024 + k] * wv;
;   }
.Lada_nopf:
	v_add_u32_e32 v96, s12, v74
	v_add_u32_e32 v114, 0x10000, v96
	s_mov_b64 s[14:15], 0x30000
	ds_read_b64 v[0:1], v96
	ds_read_b64 v[2:3], v96 offset:4096
	ds_read_b64 v[4:5], v96 offset:8192
	ds_read_b64 v[6:7], v96 offset:12288
	ds_read_b64 v[8:9], v96 offset:16384
	ds_read_b64 v[10:11], v96 offset:20480
	ds_read_b64 v[14:15], v96 offset:24576
	ds_read_b64 v[16:17], v96 offset:28672
	ds_read_b64 v[18:19], v96 offset:32768
	ds_read_b64 v[22:23], v96 offset:36864
	ds_read_b64 v[24:25], v96 offset:40960
	ds_read_b64 v[26:27], v96 offset:45056
	ds_read_b64 v[30:31], v96 offset:49152
	ds_read_b64 v[32:33], v96 offset:53248
	ds_read_b64 v[34:35], v96 offset:57344
	ds_read_b64 v[38:39], v96 offset:61440
	ds_read_b64 v[40:41], v114
	ds_read_b64 v[42:43], v96 offset:8
	ds_read_b64 v[46:47], v96 offset:4104
	ds_read_b64 v[48:49], v96 offset:8200
	ds_read_b64 v[50:51], v96 offset:12296
	ds_read_b64 v[54:55], v96 offset:16392
	ds_read_b64 v[56:57], v96 offset:20488
	ds_read_b64 v[58:59], v96 offset:24584
	ds_read_b64 v[62:63], v96 offset:28680
	ds_read_b64 v[64:65], v96 offset:32776
	ds_read_b64 v[66:67], v96 offset:36872
	ds_read_b64 v[70:71], v96 offset:40968
	ds_read_b64 v[98:99], v96 offset:45064
	ds_read_b64 v[100:101], v96 offset:49160
	ds_read_b64 v[102:103], v96 offset:53256
	ds_read_b64 v[104:105], v96 offset:57352
	ds_read_b64 v[106:107], v96 offset:61448
	ds_read_b64 v[108:109], v114 offset:8
	s_waitcnt lgkmcnt(15)
	v_fmac_f32_e32 v12, v116, v0
	v_fmac_f32_e32 v13, v116, v2
	v_fmac_f32_e32 v20, v116, v4
	v_fmac_f32_e32 v21, v116, v6
	v_fmac_f32_e32 v28, v116, v8
	v_fmac_f32_e32 v29, v116, v10
	v_fmac_f32_e32 v36, v116, v14
	v_fmac_f32_e32 v37, v116, v16
	v_fmac_f32_e32 v44, v116, v18
	v_fmac_f32_e32 v45, v116, v22
	v_fmac_f32_e32 v52, v116, v24
	v_fmac_f32_e32 v53, v116, v26
	v_fmac_f32_e32 v60, v116, v30
	v_fmac_f32_e32 v61, v116, v32
	v_fmac_f32_e32 v68, v116, v34
	v_fmac_f32_e32 v69, v116, v38
	v_fmac_f32_e32 v81, v116, v40
	v_fmac_f32_e32 v12, v117, v1
	v_fmac_f32_e32 v13, v117, v3
	v_fmac_f32_e32 v20, v117, v5
	v_fmac_f32_e32 v21, v117, v7
	v_fmac_f32_e32 v28, v117, v9
	v_fmac_f32_e32 v29, v117, v11
	v_fmac_f32_e32 v36, v117, v15
	v_fmac_f32_e32 v37, v117, v17
	v_fmac_f32_e32 v44, v117, v19
	v_fmac_f32_e32 v45, v117, v23
	v_fmac_f32_e32 v52, v117, v25
	v_fmac_f32_e32 v53, v117, v27
	v_fmac_f32_e32 v60, v117, v31
	v_fmac_f32_e32 v61, v117, v33
	v_fmac_f32_e32 v68, v117, v35
	v_fmac_f32_e32 v69, v117, v39
	v_fmac_f32_e32 v81, v117, v41
	ds_read_b64 v[0:1], v96 offset:16
	ds_read_b64 v[2:3], v96 offset:4112
	ds_read_b64 v[4:5], v96 offset:8208
	ds_read_b64 v[6:7], v96 offset:12304
	ds_read_b64 v[8:9], v96 offset:16400
	ds_read_b64 v[10:11], v96 offset:20496
	ds_read_b64 v[14:15], v96 offset:24592
	ds_read_b64 v[16:17], v96 offset:28688
	ds_read_b64 v[18:19], v96 offset:32784
	ds_read_b64 v[22:23], v96 offset:36880
	ds_read_b64 v[24:25], v96 offset:40976
	ds_read_b64 v[26:27], v96 offset:45072
	ds_read_b64 v[30:31], v96 offset:49168
	ds_read_b64 v[32:33], v96 offset:53264
	ds_read_b64 v[34:35], v96 offset:57360
	ds_read_b64 v[38:39], v96 offset:61456
	ds_read_b64 v[40:41], v114 offset:16
	s_waitcnt lgkmcnt(15)
	v_fmac_f32_e32 v12, v118, v42
	v_fmac_f32_e32 v13, v118, v46
	v_fmac_f32_e32 v20, v118, v48
	v_fmac_f32_e32 v21, v118, v50
	v_fmac_f32_e32 v28, v118, v54
	v_fmac_f32_e32 v29, v118, v56
	v_fmac_f32_e32 v36, v118, v58
	v_fmac_f32_e32 v37, v118, v62
	v_fmac_f32_e32 v44, v118, v64
	v_fmac_f32_e32 v45, v118, v66
	v_fmac_f32_e32 v52, v118, v70
	v_fmac_f32_e32 v53, v118, v98
	v_fmac_f32_e32 v60, v118, v100
	v_fmac_f32_e32 v61, v118, v102
	v_fmac_f32_e32 v68, v118, v104
	v_fmac_f32_e32 v69, v118, v106
	v_fmac_f32_e32 v81, v118, v108
	v_fmac_f32_e32 v12, v119, v43
	v_fmac_f32_e32 v13, v119, v47
	v_fmac_f32_e32 v20, v119, v49
	v_fmac_f32_e32 v21, v119, v51
	v_fmac_f32_e32 v28, v119, v55
	v_fmac_f32_e32 v29, v119, v57
	v_fmac_f32_e32 v36, v119, v59
	v_fmac_f32_e32 v37, v119, v63
	v_fmac_f32_e32 v44, v119, v65
	v_fmac_f32_e32 v45, v119, v67
	v_fmac_f32_e32 v52, v119, v71
	v_fmac_f32_e32 v53, v119, v99
	v_fmac_f32_e32 v60, v119, v101
	v_fmac_f32_e32 v61, v119, v103
	v_fmac_f32_e32 v68, v119, v105
	v_fmac_f32_e32 v69, v119, v107
	v_fmac_f32_e32 v81, v119, v109
	ds_read_b64 v[42:43], v96 offset:24
	ds_read_b64 v[46:47], v96 offset:4120
	ds_read_b64 v[48:49], v96 offset:8216
	ds_read_b64 v[50:51], v96 offset:12312
	ds_read_b64 v[54:55], v96 offset:16408
	ds_read_b64 v[56:57], v96 offset:20504
	ds_read_b64 v[58:59], v96 offset:24600
	ds_read_b64 v[62:63], v96 offset:28696
	ds_read_b64 v[64:65], v96 offset:32792
	ds_read_b64 v[66:67], v96 offset:36888
	ds_read_b64 v[70:71], v96 offset:40984
	ds_read_b64 v[98:99], v96 offset:45080
	ds_read_b64 v[100:101], v96 offset:49176
	ds_read_b64 v[102:103], v96 offset:53272
	ds_read_b64 v[104:105], v96 offset:57368
	ds_read_b64 v[106:107], v96 offset:61464
	ds_read_b64 v[108:109], v114 offset:24
	s_waitcnt lgkmcnt(15)
; DI void ada_tile(const Params& p, int layer, int cg64, char* lds) {
;     ...
; #pragma unroll 8
;   for (int kk = 0; kk < 256; ++kk) {
;     int k = kq * 256 + kk;
;     float wv = w[(size_t)k * 6144];
; #pragma unroll
;     for (int i = 0; i < 17; ++i) acc[i] += sc[i * 1024 + k] * wv;
;   }
;   __syncthreads();
;   float* red = (float*)lds;
; #pragma unroll
;   for (int i = 0; i < 17; ++i) red[(kq * 17 + i) * 64 + col] = acc[i];
;   __syncthreads();
;   float* mod = (float*)(p.ws + O_MOD) + (size_t)layer * 17 * 6144;
;   for (int e = tid; e < 17 * 64; e += 256) {
;     int bi = e >> 6, cc = e & 63;
;     float s = red[(0 * 17 + bi) * 64 + cc] + red[(1 * 17 + bi) * 64 + cc] + red[(2 * 17 + bi) * 64 + cc] +
;               red[(3 * 17 + bi) * 64 + cc];
;     int nn = cg64 * 64 + cc;
;     mod[bi * 6144 + nn] = s + p.ada_b[layer * 6144 + nn];
	v_fmac_f32_e32 v12, v120, v0
	v_fmac_f32_e32 v13, v120, v2
	v_fmac_f32_e32 v20, v120, v4
	v_fmac_f32_e32 v21, v120, v6
	v_fmac_f32_e32 v28, v120, v8
	v_fmac_f32_e32 v29, v120, v10
	v_fmac_f32_e32 v36, v120, v14
	v_fmac_f32_e32 v37, v120, v16
	v_fmac_f32_e32 v44, v120, v18
	v_fmac_f32_e32 v45, v120, v22
	v_fmac_f32_e32 v52, v120, v24
	v_fmac_f32_e32 v53, v120, v26
	v_fmac_f32_e32 v60, v120, v30
	v_fmac_f32_e32 v61, v120, v32
	v_fmac_f32_e32 v68, v120, v34
	v_fmac_f32_e32 v69, v120, v38
	v_fmac_f32_e32 v81, v120, v40
	v_fmac_f32_e32 v12, v121, v1
	v_fmac_f32_e32 v13, v121, v3
	v_fmac_f32_e32 v20, v121, v5
	v_fmac_f32_e32 v21, v121, v7
	v_fmac_f32_e32 v28, v121, v9
	v_fmac_f32_e32 v29, v121, v11
	v_fmac_f32_e32 v36, v121, v15
	v_fmac_f32_e32 v37, v121, v17
	v_fmac_f32_e32 v44, v121, v19
	v_fmac_f32_e32 v45, v121, v23
	v_fmac_f32_e32 v52, v121, v25
	v_fmac_f32_e32 v53, v121, v27
	v_fmac_f32_e32 v60, v121, v31
	v_fmac_f32_e32 v61, v121, v33
	v_fmac_f32_e32 v68, v121, v35
	v_fmac_f32_e32 v69, v121, v39
	v_fmac_f32_e32 v81, v121, v41
	s_waitcnt lgkmcnt(0)
	v_fmac_f32_e32 v12, v122, v42
	v_fmac_f32_e32 v13, v122, v46
	v_fmac_f32_e32 v20, v122, v48
	v_fmac_f32_e32 v21, v122, v50
	v_fmac_f32_e32 v28, v122, v54
	v_fmac_f32_e32 v29, v122, v56
	v_fmac_f32_e32 v36, v122, v58
	v_fmac_f32_e32 v37, v122, v62
	v_fmac_f32_e32 v44, v122, v64
	v_fmac_f32_e32 v45, v122, v66
	v_fmac_f32_e32 v52, v122, v70
	v_fmac_f32_e32 v53, v122, v98
	v_fmac_f32_e32 v60, v122, v100
	v_fmac_f32_e32 v61, v122, v102
	v_fmac_f32_e32 v68, v122, v104
	v_fmac_f32_e32 v69, v122, v106
	v_fmac_f32_e32 v81, v122, v108
	v_fmac_f32_e32 v12, v123, v43
	v_fmac_f32_e32 v13, v123, v47
	v_fmac_f32_e32 v20, v123, v49
	v_fmac_f32_e32 v21, v123, v51
	v_fmac_f32_e32 v28, v123, v55
	v_fmac_f32_e32 v29, v123, v57
	v_fmac_f32_e32 v36, v123, v59
	v_fmac_f32_e32 v37, v123, v63
	v_fmac_f32_e32 v44, v123, v65
	v_fmac_f32_e32 v45, v123, v67
	v_fmac_f32_e32 v52, v123, v71
	v_fmac_f32_e32 v53, v123, v99
	v_fmac_f32_e32 v60, v123, v101
	v_fmac_f32_e32 v61, v123, v103
	v_fmac_f32_e32 v68, v123, v105
	v_fmac_f32_e32 v69, v123, v107
	v_fmac_f32_e32 v81, v123, v109
	v_lshl_add_u64 v[82:83], v[82:83], 0, s[14:15]
	s_add_i32 s12, s12, 32
	s_cmpk_eq_i32 s12, 0x400
	s_cbranch_scc0 .LBB0_36
	s_movk_i32 s12, 0x1100
	v_mul_lo_u32 v0, v79, s12
	v_lshlrev_b32_e32 v1, 2, v76
	s_movk_i32 s12, 0x440
	v_add3_u32 v0, s88, v0, v1
	v_cmp_gt_i32_e32 vcc, s12, v78
	s_barrier
	ds_write2st64_b32 v0, v12, v13 offset1:1
	ds_write2st64_b32 v0, v20, v21 offset0:2 offset1:3
	ds_write2st64_b32 v0, v28, v29 offset0:4 offset1:5
	ds_write2st64_b32 v0, v36, v37 offset0:6 offset1:7
	ds_write2st64_b32 v0, v44, v45 offset0:8 offset1:9
	ds_write2st64_b32 v0, v52, v53 offset0:10 offset1:11
	ds_write2st64_b32 v0, v60, v61 offset0:12 offset1:13
	ds_write2st64_b32 v0, v68, v69 offset0:14 offset1:15
	ds_write_b32 v0, v81 offset:4096
	s_waitcnt lgkmcnt(0)
	s_barrier
	s_and_saveexec_b64 s[12:13], vcc
	s_cbranch_execz .LBB0_40
	s_and_b64 s[14:15], s[8:9], exec
	s_cselect_b32 s14, 0x66000, 0
	s_add_u32 s14, s43, s14
	s_addc_u32 s15, s44, 0
	s_and_b64 s[8:9], s[8:9], exec
	s_cselect_b32 s8, 0x1800, 0
	v_add_u32_e32 v74, s8, v80
	v_lshl_add_u64 v[0:1], v[74:75], 2, s[58:59]
	v_lshl_add_u32 v2, v76, 2, s88
	s_mov_b64 s[8:9], 0

; DI float bf2f(u16 v) { return __uint_as_float(((u32)v) << 16); }
; DI void prep_mla(const Params& p, int layer, int tm, int which, int nt, char* lds) {
;     ...
;   if (which == 1 && nt == 0) {
;     u16* KR = (u16*)(p.ws + O_KR);
;     for (int e = tid; e < 256 * 16; e += 256) {
;       int rr = e >> 4, i = e & 15, row = m0 + rr;
;       float cs = 1.f, sn = 0.f;
;       if (row < NLAT) { float2 t = tab[(row & 4095) * 64 + 48 + i]; cs = t.x; sn = t.y; }
;       float x1 = bf2f(Z[(size_t)row * ZW + C_DKR + i]), x2 = bf2f(Z[(size_t)row * ZW + C_DKR + 16 + i]);
;       KR[(size_t)row * 32 + i] = f2bf(x1 * cs - x2 * sn);
;       KR[(size_t)row * 32 + 16 + i] = f2bf(x1 * sn + x2 * cs);
.LBB0_234:
	s_cmp_eq_u32 s17, 0
	s_cselect_b64 s[2:3], -1, 0
	s_xor_b64 s[0:1], s[0:1], -1
	s_and_b64 s[2:3], s[2:3], s[0:1]
	s_mov_b64 s[0:1], exec
	s_and_b64 s[2:3], s[0:1], s[2:3]
	v_mov_b32_e32 v171, v230
	v_mov_b32_e32 v184, 0x3727c5ac
	s_mov_b64 exec, s[2:3]
	s_cbranch_execz .LBB0_239
	v_and_b32_e32 v2, 15, v158
	v_readlane_b32 s2, v250, 61
	v_lshlrev_b32_e32 v0, 1, v2
	v_readlane_b32 s3, v250, 62
	v_ashrrev_i32_e32 v3, 4, v158
	v_add_u32_e32 v6, s16, v3
	v_lshl_add_u64 v[4:5], s[2:3], 0, v[0:1]
	v_ashrrev_i32_e32 v7, 31, v6
	v_lshlrev_b64 v[8:9], 6, v[6:7]
	v_lshl_add_u64 v[4:5], v[4:5], 0, v[8:9]
	v_mov_b64_e32 v[10:11], s[50:51]
	v_mad_i64_i32 v[10:11], s[8:9], v6, s87, v[10:11]
	v_lshl_add_u64 v[10:11], v[10:11], 0, v[0:1]
	v_add_co_u32_e32 v10, vcc, 0x1000, v10
	s_nop 1
	v_addc_co_u32_e32 v11, vcc, 0, v11, vcc
	v_cmp_gt_i32_e32 vcc, s55, v6
	v_lshlrev_b32_e32 v76, 6, v6
	s_mov_b32 s10, 0x3ffc0
	v_and_or_b32 v76, v76, s10, v2
	v_readlane_b32 s10, v250, 59
	v_lshlrev_b32_e32 v76, 3, v76
	v_readlane_b32 s11, v250, 60
	v_mov_b32_e32 v12, 1.0
	v_mov_b32_e32 v13, 0
	v_mov_b32_e32 v14, 1.0
	v_mov_b32_e32 v15, 0
	v_mov_b32_e32 v16, 1.0
	v_mov_b32_e32 v17, 0
	v_mov_b32_e32 v18, 1.0
	v_mov_b32_e32 v19, 0
	v_mov_b32_e32 v20, 1.0
	v_mov_b32_e32 v21, 0
	v_mov_b32_e32 v22, 1.0
	v_mov_b32_e32 v23, 0
	v_mov_b32_e32 v24, 1.0
	v_mov_b32_e32 v25, 0
	v_mov_b32_e32 v26, 1.0
	v_mov_b32_e32 v27, 0
	v_mov_b32_e32 v28, 1.0
	v_mov_b32_e32 v29, 0
	v_mov_b32_e32 v30, 1.0
	v_mov_b32_e32 v31, 0
	v_mov_b32_e32 v32, 1.0
	v_mov_b32_e32 v33, 0
	v_mov_b32_e32 v34, 1.0
	v_mov_b32_e32 v35, 0
	v_mov_b32_e32 v36, 1.0
	v_mov_b32_e32 v37, 0
	v_mov_b32_e32 v38, 1.0
	v_mov_b32_e32 v39, 0
	v_mov_b32_e32 v40, 1.0
	v_mov_b32_e32 v41, 0
	v_mov_b32_e32 v42, 1.0
	v_mov_b32_e32 v43, 0
	s_and_saveexec_b64 s[100:101], vcc
	global_load_dwordx2 v[12:13], v76, s[10:11] offset:384
	v_add_u32_e32 v76, 0x2000, v76
	global_load_dwordx2 v[14:15], v76, s[10:11] offset:384
	v_add_u32_e32 v76, 0x2000, v76
	global_load_dwordx2 v[16:17], v76, s[10:11] offset:384
	v_add_u32_e32 v76, 0x2000, v76
	global_load_dwordx2 v[18:19], v76, s[10:11] offset:384
	v_add_u32_e32 v76, 0x2000, v76
	global_load_dwordx2 v[20:21], v76, s[10:11] offset:384
	v_add_u32_e32 v76, 0x2000, v76
	global_load_dwordx2 v[22:23], v76, s[10:11] offset:384
	v_add_u32_e32 v76, 0x2000, v76
	global_load_dwordx2 v[24:25], v76, s[10:11] offset:384
	v_add_u32_e32 v76, 0x2000, v76
	global_load_dwordx2 v[26:27], v76, s[10:11] offset:384
	v_add_u32_e32 v76, 0x2000, v76
	global_load_dwordx2 v[28:29], v76, s[10:11] offset:384
	v_add_u32_e32 v76, 0x2000, v76
	global_load_dwordx2 v[30:31], v76, s[10:11] offset:384
	v_add_u32_e32 v76, 0x2000, v76
	global_load_dwordx2 v[32:33], v76, s[10:11] offset:384
	v_add_u32_e32 v76, 0x2000, v76
	global_load_dwordx2 v[34:35], v76, s[10:11] offset:384
	v_add_u32_e32 v76, 0x2000, v76
	global_load_dwordx2 v[36:37], v76, s[10:11] offset:384
	v_add_u32_e32 v76, 0x2000, v76
	global_load_dwordx2 v[38:39], v76, s[10:11] offset:384
	v_add_u32_e32 v76, 0x2000, v76
	global_load_dwordx2 v[40:41], v76, s[10:11] offset:384
	v_add_u32_e32 v76, 0x2000, v76
	global_load_dwordx2 v[42:43], v76, s[10:11] offset:384
	s_mov_b64 exec, s[100:101]
	s_lshl_b32 s8, s87, 4
	s_mov_b32 s9, 0
	global_load_ushort v44, v[10:11], off offset:1312
	global_load_ushort v60, v[10:11], off offset:1344
	v_lshl_add_u64 v[10:11], v[10:11], 0, s[8:9]
	global_load_ushort v45, v[10:11], off offset:1312
	global_load_ushort v61, v[10:11], off offset:1344
	v_lshl_add_u64 v[10:11], v[10:11], 0, s[8:9]
	global_load_ushort v46, v[10:11], off offset:1312
	global_load_ushort v62, v[10:11], off offset:1344
	v_lshl_add_u64 v[10:11], v[10:11], 0, s[8:9]
	global_load_ushort v47, v[10:11], off offset:1312
	global_load_ushort v63, v[10:11], off offset:1344
	v_lshl_add_u64 v[10:11], v[10:11], 0, s[8:9]
	global_load_ushort v48, v[10:11], off offset:1312
	global_load_ushort v64, v[10:11], off offset:1344
	v_lshl_add_u64 v[10:11], v[10:11], 0, s[8:9]
	global_load_ushort v49, v[10:11], off offset:1312
	global_load_ushort v65, v[10:11], off offset:1344
	v_lshl_add_u64 v[10:11], v[10:11], 0, s[8:9]
	global_load_ushort v50, v[10:11], off offset:1312
	global_load_ushort v66, v[10:11], off offset:1344
	v_lshl_add_u64 v[10:11], v[10:11], 0, s[8:9]
	global_load_ushort v51, v[10:11], off offset:1312
	global_load_ushort v67, v[10:11], off offset:1344
	v_lshl_add_u64 v[10:11], v[10:11], 0, s[8:9]
	global_load_ushort v52, v[10:11], off offset:1312
	global_load_ushort v68, v[10:11], off offset:1344
	v_lshl_add_u64 v[10:11], v[10:11], 0, s[8:9]
	global_load_ushort v53, v[10:11], off offset:1312
	global_load_ushort v69, v[10:11], off offset:1344
	v_lshl_add_u64 v[10:11], v[10:11], 0, s[8:9]
	global_load_ushort v54, v[10:11], off offset:1312
	global_load_ushort v70, v[10:11], off offset:1344
	v_lshl_add_u64 v[10:11], v[10:11], 0, s[8:9]
	global_load_ushort v55, v[10:11], off offset:1312
	global_load_ushort v71, v[10:11], off offset:1344
	v_lshl_add_u64 v[10:11], v[10:11], 0, s[8:9]
	global_load_ushort v56, v[10:11], off offset:1312
	global_load_ushort v72, v[10:11], off offset:1344
	v_lshl_add_u64 v[10:11], v[10:11], 0, s[8:9]
	global_load_ushort v57, v[10:11], off offset:1312
	global_load_ushort v73, v[10:11], off offset:1344
	v_lshl_add_u64 v[10:11], v[10:11], 0, s[8:9]
	global_load_ushort v58, v[10:11], off offset:1312
	global_load_ushort v74, v[10:11], off offset:1344
	v_lshl_add_u64 v[10:11], v[10:11], 0, s[8:9]
	global_load_ushort v59, v[10:11], off offset:1312
	global_load_ushort v75, v[10:11], off offset:1344
	s_mov_b64 s[2:3], 0x1000
	s_waitcnt vmcnt(30)
; DI float bf2f(u16 v) { return __uint_as_float(((u32)v) << 16); }
; DI void prep_mla(const Params& p, int layer, int tm, int which, int nt, char* lds) {
;     ...
;     for (int e = tid; e < 256 * 16; e += 256) {
;       int rr = e >> 4, i = e & 15, row = m0 + rr;
;       float cs = 1.f, sn = 0.f;
;       if (row < NLAT) { float2 t = tab[(row & 4095) * 64 + 48 + i]; cs = t.x; sn = t.y; }
;       float x1 = bf2f(Z[(size_t)row * ZW + C_DKR + i]), x2 = bf2f(Z[(size_t)row * ZW + C_DKR + 16 + i]);
;       KR[(size_t)row * 32 + i] = f2bf(x1 * cs - x2 * sn);
;       KR[(size_t)row * 32 + 16 + i] = f2bf(x1 * sn + x2 * cs);
;     }
	v_lshlrev_b32_e32 v80, 16, v44
	v_lshlrev_b32_e32 v81, 16, v60
	v_mul_f32_e32 v82, v13, v81
	v_mul_f32_e32 v83, v12, v81
	v_fma_f32 v82, v12, v80, -v82
	v_fmac_f32_e32 v83, v13, v80
	v_cvt_pk_bf16_f32 v82, v82, v82
	v_cvt_pk_bf16_f32 v83, v83, v83
	global_store_short v[4:5], v82, off
	global_store_short v[4:5], v83, off offset:32
	s_waitcnt vmcnt(30)
	v_lshlrev_b32_e32 v84, 16, v45
	v_lshlrev_b32_e32 v85, 16, v61
	v_mul_f32_e32 v86, v15, v85
	v_mul_f32_e32 v87, v14, v85
	v_fma_f32 v86, v14, v84, -v86
	v_fmac_f32_e32 v87, v15, v84
	v_cvt_pk_bf16_f32 v86, v86, v86
	v_cvt_pk_bf16_f32 v87, v87, v87
	global_store_short v[4:5], v86, off offset:1024
	global_store_short v[4:5], v87, off offset:1056
	s_waitcnt vmcnt(30)
	v_lshlrev_b32_e32 v88, 16, v46
	v_lshlrev_b32_e32 v89, 16, v62
	v_mul_f32_e32 v90, v17, v89
	v_mul_f32_e32 v91, v16, v89
	v_fma_f32 v90, v16, v88, -v90
	v_fmac_f32_e32 v91, v17, v88
	v_cvt_pk_bf16_f32 v90, v90, v90
	v_cvt_pk_bf16_f32 v91, v91, v91
	global_store_short v[4:5], v90, off offset:2048
	global_store_short v[4:5], v91, off offset:2080
	s_waitcnt vmcnt(30)
	v_lshlrev_b32_e32 v92, 16, v47
	v_lshlrev_b32_e32 v93, 16, v63
	v_mul_f32_e32 v94, v19, v93
	v_mul_f32_e32 v95, v18, v93
	v_fma_f32 v94, v18, v92, -v94
	v_fmac_f32_e32 v95, v19, v92
	v_cvt_pk_bf16_f32 v94, v94, v94
	v_cvt_pk_bf16_f32 v95, v95, v95
	global_store_short v[4:5], v94, off offset:3072
	global_store_short v[4:5], v95, off offset:3104
	v_lshl_add_u64 v[4:5], v[4:5], 0, s[2:3]
	s_waitcnt vmcnt(30)
	v_lshlrev_b32_e32 v96, 16, v48
	v_lshlrev_b32_e32 v97, 16, v64
	v_mul_f32_e32 v98, v21, v97
	v_mul_f32_e32 v99, v20, v97
	v_fma_f32 v98, v20, v96, -v98
	v_fmac_f32_e32 v99, v21, v96
	v_cvt_pk_bf16_f32 v98, v98, v98
	v_cvt_pk_bf16_f32 v99, v99, v99
	global_store_short v[4:5], v98, off
	global_store_short v[4:5], v99, off offset:32
	s_waitcnt vmcnt(30)
	v_lshlrev_b32_e32 v100, 16, v49
	v_lshlrev_b32_e32 v101, 16, v65
	v_mul_f32_e32 v102, v23, v101
	v_mul_f32_e32 v103, v22, v101
	v_fma_f32 v102, v22, v100, -v102
	v_fmac_f32_e32 v103, v23, v100
	v_cvt_pk_bf16_f32 v102, v102, v102
	v_cvt_pk_bf16_f32 v103, v103, v103
	global_store_short v[4:5], v102, off offset:1024
	global_store_short v[4:5], v103, off offset:1056
	s_waitcnt vmcnt(30)
	v_lshlrev_b32_e32 v104, 16, v50
	v_lshlrev_b32_e32 v105, 16, v66
	v_mul_f32_e32 v106, v25, v105
	v_mul_f32_e32 v107, v24, v105
	v_fma_f32 v106, v24, v104, -v106
	v_fmac_f32_e32 v107, v25, v104
	v_cvt_pk_bf16_f32 v106, v106, v106
	v_cvt_pk_bf16_f32 v107, v107, v107
	global_store_short v[4:5], v106, off offset:2048
	global_store_short v[4:5], v107, off offset:2080
	s_waitcnt vmcnt(30)
	v_lshlrev_b32_e32 v108, 16, v51
	v_lshlrev_b32_e32 v109, 16, v67
	v_mul_f32_e32 v110, v27, v109
	v_mul_f32_e32 v111, v26, v109
	v_fma_f32 v110, v26, v108, -v110
	v_fmac_f32_e32 v111, v27, v108
	v_cvt_pk_bf16_f32 v110, v110, v110
	v_cvt_pk_bf16_f32 v111, v111, v111
	global_store_short v[4:5], v110, off offset:3072
	global_store_short v[4:5], v111, off offset:3104
	v_lshl_add_u64 v[4:5], v[4:5], 0, s[2:3]
	s_waitcnt vmcnt(30)
	v_lshlrev_b32_e32 v112, 16, v52
	v_lshlrev_b32_e32 v113, 16, v68
	v_mul_f32_e32 v114, v29, v113
	v_mul_f32_e32 v115, v28, v113
	v_fma_f32 v114, v28, v112, -v114
	v_fmac_f32_e32 v115, v29, v112
	v_cvt_pk_bf16_f32 v114, v114, v114
	v_cvt_pk_bf16_f32 v115, v115, v115
	global_store_short v[4:5], v114, off
	global_store_short v[4:5], v115, off offset:32
	s_waitcnt vmcnt(30)
	v_lshlrev_b32_e32 v116, 16, v53
	v_lshlrev_b32_e32 v117, 16, v69
	v_mul_f32_e32 v118, v31, v117
	v_mul_f32_e32 v119, v30, v117
	v_fma_f32 v118, v30, v116, -v118
	v_fmac_f32_e32 v119, v31, v116
	v_cvt_pk_bf16_f32 v118, v118, v118
	v_cvt_pk_bf16_f32 v119, v119, v119
	global_store_short v[4:5], v118, off offset:1024
	global_store_short v[4:5], v119, off offset:1056
	s_waitcnt vmcnt(30)
	v_lshlrev_b32_e32 v120, 16, v54
	v_lshlrev_b32_e32 v121, 16, v70
	v_mul_f32_e32 v122, v33, v121
	v_mul_f32_e32 v123, v32, v121
	v_fma_f32 v122, v32, v120, -v122
	v_fmac_f32_e32 v123, v33, v120
	v_cvt_pk_bf16_f32 v122, v122, v122
	v_cvt_pk_bf16_f32 v123, v123, v123
	global_store_short v[4:5], v122, off offset:2048
	global_store_short v[4:5], v123, off offset:2080
	s_waitcnt vmcnt(30)
	v_lshlrev_b32_e32 v124, 16, v55
	v_lshlrev_b32_e32 v125, 16, v71
	v_mul_f32_e32 v126, v35, v125
	v_mul_f32_e32 v127, v34, v125
	v_fma_f32 v126, v34, v124, -v126
	v_fmac_f32_e32 v127, v35, v124
	v_cvt_pk_bf16_f32 v126, v126, v126
	v_cvt_pk_bf16_f32 v127, v127, v127
	global_store_short v[4:5], v126, off offset:3072
	global_store_short v[4:5], v127, off offset:3104
	v_lshl_add_u64 v[4:5], v[4:5], 0, s[2:3]
	s_waitcnt vmcnt(30)
	v_lshlrev_b32_e32 v80, 16, v56
	v_lshlrev_b32_e32 v81, 16, v72
	v_mul_f32_e32 v82, v37, v81
	v_mul_f32_e32 v83, v36, v81
	v_fma_f32 v82, v36, v80, -v82
	v_fmac_f32_e32 v83, v37, v80
	v_cvt_pk_bf16_f32 v82, v82, v82
	v_cvt_pk_bf16_f32 v83, v83, v83
	global_store_short v[4:5], v82, off
	global_store_short v[4:5], v83, off offset:32
	s_waitcnt vmcnt(30)
	v_lshlrev_b32_e32 v84, 16, v57
	v_lshlrev_b32_e32 v85, 16, v73
	v_mul_f32_e32 v86, v39, v85
	v_mul_f32_e32 v87, v38, v85
	v_fma_f32 v86, v38, v84, -v86
	v_fmac_f32_e32 v87, v39, v84
	v_cvt_pk_bf16_f32 v86, v86, v86
	v_cvt_pk_bf16_f32 v87, v87, v87
	global_store_short v[4:5], v86, off offset:1024
	global_store_short v[4:5], v87, off offset:1056
	s_waitcnt vmcnt(30)
	v_lshlrev_b32_e32 v88, 16, v58
	v_lshlrev_b32_e32 v89, 16, v74
	v_mul_f32_e32 v90, v41, v89
	v_mul_f32_e32 v91, v40, v89
	v_fma_f32 v90, v40, v88, -v90
	v_fmac_f32_e32 v91, v41, v88
	v_cvt_pk_bf16_f32 v90, v90, v90
	v_cvt_pk_bf16_f32 v91, v91, v91
	global_store_short v[4:5], v90, off offset:2048
	global_store_short v[4:5], v91, off offset:2080
	s_waitcnt vmcnt(30)
	v_lshlrev_b32_e32 v92, 16, v59
	v_lshlrev_b32_e32 v93, 16, v75
	v_mul_f32_e32 v94, v43, v93
	v_mul_f32_e32 v95, v42, v93
	v_fma_f32 v94, v42, v92, -v94
	v_fmac_f32_e32 v95, v43, v92
	v_cvt_pk_bf16_f32 v94, v94, v94
	v_cvt_pk_bf16_f32 v95, v95, v95
	global_store_short v[4:5], v94, off offset:3072
	global_store_short v[4:5], v95, off offset:3104

; DI void prep_mla(const Params& p, int layer, int tm, int which, int nt, char* lds) {
;     ...
;       for (int idx = tid; idx < 128 * 32; idx += 256) {
;         const int rr = idx >> 5, c4 = (idx & 31) * 4;
;         const int row = m0 + half * 128 + rr;
;         const float sc = rs[half * 128 + rr] * qs;
;         float o[4];
; #pragma unroll
;         for (int j = 0; j < 4; ++j) {
;           int cl = c4 + j, c = nt * 128 + cl, d = c % 96;
;           float v = Cs[rr * CSL + cl];
;           if (d >= 64 && row < NLAT) {
;             int i = d - 64;
;             if (i < 16) {
;               float2 t = tab[(row & 4095) * 64 + 48 + i];
;               float x2 = Cs[rr * CSL + cl + 16];
;               v = v * t.x - x2 * t.y;
;             } else {
;               float2 t = tab[(row & 4095) * 64 + 48 + i - 16];
;               float x1 = Cs[rr * CSL + cl - 16];
;               v = x1 * t.y + v * t.x;
;             }
;           }
;           o[j] = v * sc;
;         }
;         uint2 w;
;         w.x = pack2(o[0], o[1]); w.y = pack2(o[2], o[3]);
;         *(uint2*)(QD + (size_t)row * 384 + nt * 128 + c4) = w;
.LBB0_247:
	s_or_b64 exec, exec, s[2:3]
	s_waitcnt lgkmcnt(0)
	s_barrier
	s_and_saveexec_b64 s[12:13], s[0:1]
	s_cbranch_execz .LBB0_244
	s_lshl_b32 s31, s14, 7
	s_mov_b64 s[14:15], 0
	v_mov_b32_e32 v142, v159
	v_mov_b32_e32 v143, v158
	s_mov_b32 m0, 0
	s_branch .LBB0_251
.LBB0_251:
	v_ashrrev_i32_e32 v130, 5, v143
	v_add_u32_e32 v0, s31, v130
	v_add_u32_e32 v145, s26, v0
	v_lshl_add_u32 v0, v0, 2, s19
	v_and_b32_e32 v144, 0x7c, v142
	ds_read_b32 v146, v0
	v_lshlrev_b32_e32 v0, 6, v145
	v_and_b32_e32 v138, 0x3ffc0, v0
	v_or_b32_e32 v0, s27, v144
	s_mov_b32 s2, 0x2aaaaab
	v_mul_hi_u32 v131, v0, s2
	v_mul_u32_u24_e32 v131, 0x60, v131
	s_movk_i32 s2, 0x210
	v_sub_u32_e32 v0, v0, v131
	v_lshlrev_b32_e32 v131, 2, v144
	v_mul_lo_u32 v130, v130, s2
	v_add3_u32 v147, s88, v131, v130
	ds_read_b128 v[170:173], v147
	v_cmp_gt_i32_e32 vcc, s55, v145
	v_cmp_lt_u32_e64 s[2:3], 63, v0
	s_and_b64 s[2:3], s[2:3], vcc
	s_and_saveexec_b64 s[16:17], s[2:3]
	s_cbranch_execz .Lprepq_norot
	s_movk_i32 s2, 0x4f
	v_cmp_lt_u32_e64 s[2:3], s2, v0
	v_readlane_b32 s20, v250, 59
	v_readlane_b32 s21, v250, 60
	v_mov_b32_e32 v161, 0xffffffe0
	v_cndmask_b32_e64 v160, -16, v161, s[2:3]
	v_add3_u32 v0, v138, v0, v160
	s_cmp_lg_u32 m0, 0
	s_cbranch_scc1 .Lprepq_have
	v_lshl_add_u64 v[156:157], v[0:1], 3, s[20:21]
	global_load_dwordx4 v[148:151], v[156:157], off
	global_load_dwordx4 v[152:155], v[156:157], off offset:16
	s_waitcnt vmcnt(0)
.Lprepq_have:
	v_mov_b32_e32 v161, 0xffffffc0
	v_cndmask_b32_e64 v160, 64, v161, s[2:3]
	v_add_u32_e32 v160, v147, v160
	ds_read_b128 v[166:169], v160
	s_waitcnt vmcnt(1) lgkmcnt(0)
	v_mul_f32_e32 v161, v166, v149
	v_mul_f32_e32 v170, v170, v148
	v_cndmask_b32_e64 v161, -v161, v161, s[2:3]
	v_add_f32_e32 v170, v170, v161
	v_mul_f32_e32 v161, v167, v151
	v_mul_f32_e32 v171, v171, v150
	v_cndmask_b32_e64 v161, -v161, v161, s[2:3]
	v_add_f32_e32 v171, v171, v161
	v_mul_f32_e32 v161, v168, v153
	v_mul_f32_e32 v172, v172, v152
	v_cndmask_b32_e64 v161, -v161, v161, s[2:3]
	v_add_f32_e32 v172, v172, v161
	v_mul_f32_e32 v161, v169, v155
	v_mul_f32_e32 v173, v173, v154
	v_cndmask_b32_e64 v161, -v161, v161, s[2:3]
	v_add_f32_e32 v173, v173, v161
	s_add_u32 m0, m0, 1
	s_cmp_eq_u32 m0, 16
	s_cbranch_scc1 .Lprepq_norot
	v_add_u32_e32 v0, 0x200, v0
	v_lshl_add_u64 v[156:157], v[0:1], 3, s[20:21]
	global_load_dwordx4 v[148:151], v[156:157], off
	global_load_dwordx4 v[152:155], v[156:157], off offset:16
